# same as previous plus gridDim==256 guards on the tail conversion and the PREP start offset
# speedup vs baseline: 1.0169x; 1.0032x over previous
; __device__ __forceinline__ void fp8_convert_range(const Frame& F, int l, int start, int stride, int limit) {
;     ...
;     int it = start;
;     bool ha = it < limit && witem_decode(F, l, it, ta);
;     if (ha) witem_load(ta, F.wave, F.lane, va);
.Lcvt_entry:
	s_lshl_b32 s4, s96, 5
	v_readlane_b32 s0, v250, 32
	s_cmp_lg_u32 s101, 0
	s_cbranch_scc1 .Lcv32_t
	s_cmp_lg_u32 s96, 0
	s_cselect_b32 s1, 9, 0
	s_cmp_eq_u32 s81, 0x100
	s_cselect_b32 s1, s1, 0
	s_add_i32 s0, s0, s1
	s_branch .Lcv32_e

; #define LAS __attribute__((address_space(3)))
; __device__ __forceinline__ void witem_load(const WItem& t, int wave, int lane, f32x4 (&v)[16]) {
;     const float* wp = t.W + (size_t)(t.k0 + 32 * wave + 16 * (lane >> 5)) * t.N + t.n0 + 4 * (lane & 31);
; #pragma unroll
;     for (int q = 0; q < 16; ++q) v[q] = __builtin_nontemporal_load((const f32x4*)(wp + (size_t)q * t.N));
; __device__ __forceinline__ void witem_store(const Frame& F, const WItem& t, const f32x4 (&v)[16], LAS unsigned char* tile) {
;     const int i = F.lane & 31, hi = F.lane >> 5;
; #pragma unroll
;     for (int j = 0; j < 4; ++j) {
;         u32x4 o;
; #pragma unroll
;         for (int d = 0; d < 4; ++d) { int r = __builtin_amdgcn_cvt_pk_fp8_f32(v[4 * d][j] * t.scale, v[4 * d + 1][j] * t.scale, 0, false);
;             r = __builtin_amdgcn_cvt_pk_fp8_f32(v[4 * d + 2][j] * t.scale, v[4 * d + 3][j] * t.scale, r, true); o[d] = (unsigned)r; }
;         *(LAS u32x4*)(tile + (32 * j + i) * 272 + 32 * F.wave + 16 * hi) = o;
;     }
;     __syncthreads();
;     const int c = F.tid & 15;
; #pragma unroll
;     for (int pass = 0; pass < 4; ++pass) { const int n = (F.tid >> 4) + 32 * pass, rho = (n & 3) * 32 + (n >> 2);
;         const u32x4 o = *(const LAS u32x4*)(tile + rho * 272 + 16 * c);
.Lcv34_e:
	v_sub_f32_e32 v1, v1, v3
	v_floor_f32_e32 v1, v1
	v_cmp_gt_f32_e32 vcc, s6, v1
	s_and_b64 s[6:7], vcc, exec
	s_cselect_b32 s7, 0xffffffc0, 0
	s_lshl_b32 s6, s8, 5
	s_add_i32 s8, s6, s9
	v_or_b32_e32 v2, s8, v54
	v_ashrrev_i32_e32 v3, 31, v2
	v_lshlrev_b64 v[2:3], 13, v[2:3]
	v_lshl_add_u64 v[2:3], s[26:27], 0, v[2:3]
	v_lshl_add_u64 v[2:3], s[44:45], 2, v[2:3]
	v_lshl_add_u64 v[38:39], v[2:3], 0, v[198:199]
	v_cndmask_b32_e32 v55, 0, v233, vcc
	v_add_co_u32_e32 v6, vcc, s70, v38
	s_movk_i32 s8, 0x4000
	s_nop 0
	v_addc_co_u32_e32 v7, vcc, 0, v39, vcc
	v_add_co_u32_e32 v10, vcc, s8, v38
	s_movk_i32 s8, 0x6000
	s_nop 0
	v_addc_co_u32_e32 v11, vcc, 0, v39, vcc
	v_add_co_u32_e32 v14, vcc, s8, v38
	s_mov_b32 s8, 0x8000
	s_nop 0
	v_addc_co_u32_e32 v15, vcc, 0, v39, vcc
	v_add_co_u32_e32 v18, vcc, s8, v38
	s_mov_b32 s8, 0xa000
	s_nop 0
	v_addc_co_u32_e32 v19, vcc, 0, v39, vcc
	v_add_co_u32_e32 v22, vcc, s8, v38
	s_mov_b32 s8, 0xc000
	s_nop 0
	v_addc_co_u32_e32 v23, vcc, 0, v39, vcc
	v_add_co_u32_e32 v26, vcc, s8, v38
	s_mov_b32 s8, 0xe000
	s_nop 0
	v_addc_co_u32_e32 v27, vcc, 0, v39, vcc
	v_add_co_u32_e32 v30, vcc, s8, v38
	s_mov_b32 s8, 0x12000
	s_nop 0
	v_addc_co_u32_e32 v31, vcc, 0, v39, vcc
	v_add_co_u32_e32 v34, vcc, s71, v38
	v_add_f32_e32 v1, v1, v55
	s_nop 0
	v_addc_co_u32_e32 v35, vcc, 0, v39, vcc
	v_add_co_u32_e32 v40, vcc, s8, v38
	s_mov_b32 s8, 0x14000
	s_nop 0
	v_addc_co_u32_e32 v41, vcc, 0, v39, vcc
	v_add_co_u32_e32 v42, vcc, s8, v38
	s_mov_b32 s8, 0x16000
	s_nop 0
	v_addc_co_u32_e32 v43, vcc, 0, v39, vcc
	v_add_co_u32_e32 v44, vcc, s8, v38
	s_mov_b32 s8, 0x18000
	s_nop 0
	v_addc_co_u32_e32 v45, vcc, 0, v39, vcc
	v_add_co_u32_e32 v46, vcc, s8, v38
	s_mov_b32 s8, 0x1a000
	s_nop 0
	v_addc_co_u32_e32 v47, vcc, 0, v39, vcc
	v_add_co_u32_e32 v48, vcc, s8, v38
	s_mov_b32 s8, 0x1c000
	s_nop 0
	v_addc_co_u32_e32 v49, vcc, 0, v39, vcc
	global_load_dwordx4 v[2:5], v[38:39], off nt
	s_nop 0
	global_load_dwordx4 v[6:9], v[6:7], off nt
	s_nop 0
	global_load_dwordx4 v[10:13], v[10:11], off nt
	s_nop 0
	global_load_dwordx4 v[14:17], v[14:15], off nt
	s_nop 0
	global_load_dwordx4 v[18:21], v[18:19], off nt
	s_nop 0
	global_load_dwordx4 v[22:25], v[22:23], off nt
	s_nop 0
	global_load_dwordx4 v[26:29], v[26:27], off nt
	s_nop 0
	global_load_dwordx4 v[30:33], v[30:31], off nt
	s_nop 0
	global_load_dwordx4 v[34:37], v[34:35], off nt
	s_nop 0
	global_load_dwordx4 v[50:53], v[40:41], off nt
	global_load_dwordx4 v[62:65], v[42:43], off nt
	global_load_dwordx4 v[70:73], v[44:45], off nt
	global_load_dwordx4 v[82:85], v[46:47], off nt
	global_load_dwordx4 v[86:89], v[48:49], off nt
	v_add_co_u32_e32 v40, vcc, s8, v38
	s_mov_b32 s8, 0x1e000
	s_nop 0
	v_addc_co_u32_e32 v41, vcc, 0, v39, vcc
	v_add_co_u32_e32 v38, vcc, s8, v38
	v_exp_f32_e32 v1, v1
	s_nop 0
	v_addc_co_u32_e32 v39, vcc, 0, v39, vcc
	global_load_dwordx4 v[94:97], v[40:41], off nt
	global_load_dwordx4 v[102:105], v[38:39], off nt
	v_ldexp_f32 v146, v1, s7
	v_or_b32_e32 v1, s6, v54
	s_add_i32 s6, s6, 0
	v_and_b32_e32 v38, 31, v0
	v_mov_b32_e32 v39, s6
	s_movk_i32 s6, 0x110
	v_lshlrev_b32_e32 v40, 5, v131
	v_mad_u32_u24 v38, v38, s6, v39
	v_lshlrev_b32_e32 v39, 4, v0
	v_and_b32_e32 v40, 0x60, v40
	v_ashrrev_i32_e32 v41, 6, v0
	v_lshrrev_b32_e32 v45, 2, v134
	v_lshrrev_b32_e32 v48, 2, v135
	v_and_b32_e32 v132, 0xf0, v39
	v_add_u32_e32 v41, v40, v41
	v_lshlrev_b32_e32 v42, 2, v131
	v_lshrrev_b32_e32 v43, 1, v131
	v_add_u32_e32 v45, v40, v45
	v_lshlrev_b32_e32 v46, 2, v134
	v_add_u32_e32 v48, v40, v48
	v_lshlrev_b32_e32 v49, 2, v135
	v_add_u32_e32 v40, v40, v56
	v_lshlrev_b32_e32 v56, 2, v136
	v_add_u32_e32 v39, 0, v132
	v_mul_lo_u32 v41, v41, s6
	v_and_b32_e32 v42, 16, v42
	v_and_b32_e32 v43, 12, v43
	v_and_b32_e32 v44, 0x63, v131
	v_mul_lo_u32 v45, v45, s6
	v_and_b32_e32 v46, 16, v46
	v_and_b32_e32 v47, 0x63, v134
	v_mul_lo_u32 v48, v48, s6
	v_and_b32_e32 v49, 16, v49
	v_and_b32_e32 v55, 0x63, v135
	v_mul_lo_u32 v40, v40, s6
	v_and_b32_e32 v56, 16, v56
	v_or3_b32 v137, v42, v44, v43
	v_or3_b32 v138, v47, v46, v43
	v_or3_b32 v139, v55, v49, v43
	v_or3_b32 v140, v57, v56, v43
	v_add_u32_e32 v141, v38, v54
	v_add_u32_e32 v142, v39, v41
	v_add_u32_e32 v143, v39, v45
	v_add_u32_e32 v144, v39, v48
	v_add_u32_e32 v145, v39, v40
	v_readlane_b32 s6, v250, 33
	s_cmp_lg_u32 s101, 0
	s_cbranch_scc1 .Lcv33_t
	s_cmp_lg_u32 s96, 0
	s_cselect_b32 s7, 0x240, 0
	s_cmp_eq_u32 s81, 0x100
	s_cselect_b32 s7, s7, 0
	s_add_i32 s6, s6, s7
	s_branch .Lcv33_e

; #define SEAM(k) do { if (IN(k) && IN((k) + 1)) xcd_barrier(bar, is_t0); } while (0)
; __device__ __forceinline__ void fp8_convert_range(const Frame& F, int l, int start, int stride, int limit) {
;     __syncthreads();
;     WItem ta, tb; f32x4 va[16], vb[16];
;     int it = start;
;     bool ha = it < limit && witem_decode(F, l, it, ta);
;     if (ha) witem_load(ta, F.wave, F.lane, va);
; __global__ void __launch_bounds__(NTHR, 2) fwd(Args args) {
;     ...
;         if ((PMASK & 128) && IN(pb + 5)) { for (int rep = 0; rep < REPS(128); ++rep) { F = launder(F); phase_moe<0>(F, l); if (REPS(128) > 1) __syncthreads(); } SEAM(pb + 5); }
.LBB0_2254:
	s_cmp_lt_u32 s80, 0xa0
	s_cbranch_scc1 .Ltc_skip2
	s_cmp_gt_u32 s96, 2
	s_cbranch_scc1 .Ltc_skip2
	s_cmp_lg_u32 s81, 0x100
	s_cbranch_scc1 .Ltc_skip2
	s_sub_i32 s0, s80, 0xa0
	s_add_i32 s0, s0, 0x180
	s_lshr_b32 s1, s0, 6
	s_and_b32 s3, s0, 63
	s_lshr_b32 s4, s3, 4
	s_lshl_b32 s4, s4, 8
	s_and_b32 s3, s3, 15
	s_lshl_b32 s3, s3, 7
	s_mov_b32 s5, 0
	v_writelane_b32 v248, s1, 41
	v_writelane_b32 v248, s0, 42
	v_writelane_b32 v248, s4, 43
	v_writelane_b32 v248, s3, 44
	v_writelane_b32 v248, s5, 45
	s_add_i32 s96, s96, 1
	s_lshl_b32 s28, s96, 1
	s_mov_b32 s29, 0
	s_movk_i32 s74, 0x60
	s_movk_i32 s70, 0x2000
	s_mov_b32 s71, 0x10000
	v_readfirstlane_b32 s8, v0
	s_ashr_i32 s8, s8, 6
	v_and_b32_e32 v66, 63, v0
	v_lshlrev_b32_e32 v66, 2, v66
	s_movk_i32 s100, 0x240
	s_mov_b32 s101, 2
	s_mov_b64 exec, -1
	s_branch .Lcvt_entry

; #define SEAM(k) do { if (IN(k) && IN((k) + 1)) xcd_barrier(bar, is_t0); } while (0)
; __device__ __forceinline__ void fp8_convert_range(const Frame& F, int l, int start, int stride, int limit) {
;     __syncthreads();
;     WItem ta, tb; f32x4 va[16], vb[16];
;     int it = start;
;     bool ha = it < limit && witem_decode(F, l, it, ta);
;     if (ha) witem_load(ta, F.wave, F.lane, va);
; __global__ void __launch_bounds__(NTHR, 2) fwd(Args args) {
;     ...
;         if ((PMASK & 256) && IN(pb + 6)) { for (int rep = 0; rep < REPS(256); ++rep) { F = launder(F); phase_moe<1>(F, l); if (REPS(256) > 1) __syncthreads(); } SEAM(pb + 6); }
.LBB0_2367:
	s_cmp_lt_u32 s80, 0x80
	s_cbranch_scc1 .Ltc_skip1
	s_cmp_gt_u32 s96, 2
	s_cbranch_scc1 .Ltc_skip1
	s_cmp_lg_u32 s81, 0x100
	s_cbranch_scc1 .Ltc_skip1
	s_sub_i32 s0, s80, 0x80
	s_add_i32 s0, s0, 0x0
	s_lshr_b32 s1, s0, 6
	s_and_b32 s3, s0, 63
	s_lshr_b32 s4, s3, 4
	s_lshl_b32 s4, s4, 8
	s_and_b32 s3, s3, 15
	s_lshl_b32 s3, s3, 7
	s_mov_b32 s5, 0
	v_writelane_b32 v248, s1, 41
	v_writelane_b32 v248, s0, 42
	v_writelane_b32 v248, s4, 43
	v_writelane_b32 v248, s3, 44
	v_writelane_b32 v248, s5, 45
	s_add_i32 s96, s96, 1
	s_lshl_b32 s28, s96, 1
	s_mov_b32 s29, 0
	s_movk_i32 s74, 0x80
	s_movk_i32 s70, 0x2000
	s_mov_b32 s71, 0x10000
	v_readfirstlane_b32 s8, v0
	s_ashr_i32 s8, s8, 6
	v_and_b32_e32 v66, 63, v0
	v_lshlrev_b32_e32 v66, 2, v66
	s_movk_i32 s100, 0x180
	s_mov_b32 s101, 1
	s_mov_b64 exec, -1
	s_branch .Lcvt_entry
